# v60 + w1 and w_in: next unit's phase-1 staging issued before the bf16 epilogue stores; first-iteration phase-2 wait of follow-on units counts past the stores (no in-order wait on the 16 stores there)
# speedup vs baseline: 1.0057x; 1.0027x over previous
; #define PG8_STAGE(bufoff, gbase, voff) do { _Pragma("unroll") for (int _i = 0; _i < 2; ++_i) \
;         __builtin_amdgcn_global_load_lds((const unsigned*)((const char*)(gbase) + (voff)[_i]), (LAS unsigned*)(lds + (bufoff) + ldsw + _i * 8192), 16, 0, 0); } while (0)
; #define PG8_LDA(dst, b, h) do { _Pragma("unroll") for (int m = 0; m < 4; ++m) _Pragma("unroll") for (int k = 0; k < 2; ++k) dst[m][k] = *(const LAS bf16x8*)(lds + PG8_SA(b, h) + aoff + m * 2048 + k * 1024); } while (0)
; #define PG8_LDB(dst, b, h) do { _Pragma("unroll") for (int n = 0; n < 2; ++n) _Pragma("unroll") for (int k = 0; k < 2; ++k) dst[n][k] = *(const LAS bf16x8*)(lds + PG8_SB(b, h) + boff + n * 2048 + k * 1024); } while (0)
; #define PG8_MMA(ai, bj, At, Bt) do { __builtin_amdgcn_s_setprio(1); _Pragma("unroll") for (int m = 0; m < 4; ++m) _Pragma("unroll") for (int n = 0; n < 2; ++n) _Pragma("unroll") for (int k = 0; k < 2; ++k) \
;         acc[ai][bj][m][n] = __builtin_amdgcn_mfma_f32_16x16x32_bf16(Bt[n][k], At[m][k], acc[ai][bj][m][n], 0, 0, 0); __builtin_amdgcn_s_setprio(0); } while (0)
; #define PG8_WAIT_V(n) asm volatile("s_waitcnt vmcnt(" #n ")" ::: "memory")
; #define PG8_WAIT_L(n) asm volatile("s_waitcnt lgkmcnt(" #n ")" ::: "memory")
; #define PG8_BAR __builtin_amdgcn_s_barrier()
; #define PG8_SCHED __builtin_amdgcn_sched_barrier(0)
; template <class Epi, class Sched>
; __device__ __forceinline__ void gemm_phase(LAS unsigned char* lds, const Gemm g, const Sched& S, const Epi& E) {
;     ...
;             PG8_LDB(B0, 0, 0); PG8_SCHED; PG8_LDA(At, 0, 0); PG8_STAGE(PG8_SA(1, 1), a1 + hstep, voffA);
;             PG8_WAIT_L(8); PG8_BAR; PG8_WAIT_L(0); PG8_MMA(0, 0, At, B0); PG8_BAR; PG8_SCHED;
;             PG8_LDB(B1, 0, 1); PG8_STAGE(PG8_SB(0, 0), b2, voffB);
;             PG8_BAR; PG8_WAIT_L(0); PG8_MMA(0, 1, At, B1); PG8_BAR;
;             PG8_LDA(At, 0, 1); PG8_STAGE(PG8_SA(0, 0), a2, voffA);
;             PG8_BAR; PG8_WAIT_L(0); PG8_MMA(1, 0, At, B0); PG8_BAR; PG8_SCHED;
;             PG8_STAGE(PG8_SB(0, 1), b2 + hstep, voffB);
;             PG8_WAIT_V(6); PG8_BAR; PG8_MMA(1, 1, At, B1); PG8_BAR;
.LBB0_354:
	s_add_u32 s38, s50, 0xfff80080
	s_addc_u32 s39, s51, -1
	s_cmp_eq_u32 s70, 28
	s_cselect_b32 s55, s9, s39
	s_cselect_b32 s54, s66, s38
	s_cselect_b32 s53, s43, s69
	s_cselect_b32 s52, s67, s68
	s_add_i32 m0, s29, 0xc000
	s_nop 0
	global_load_lds_dwordx4 v138, s[50:51]
	s_add_i32 m0, s29, 0xe000
	s_nop 0
	global_load_lds_dwordx4 v136, s[50:51]
	s_add_i32 s71, 0, 0x10000
	v_add_u32_e32 v156, s71, v145
	ds_read_b128 v[140:143], v156
	ds_read_b128 v[148:151], v156 offset:1024
	ds_read_b128 v[152:155], v156 offset:2048
	ds_read_b128 v[160:163], v156 offset:3072
	ds_read_b128 v[164:167], v147
	ds_read_b128 v[168:171], v147 offset:1024
	ds_read_b128 v[172:175], v147 offset:2048
	ds_read_b128 v[176:179], v147 offset:3072
	ds_read_b128 v[180:183], v147 offset:4096
	ds_read_b128 v[184:187], v147 offset:5120
	ds_read_b128 v[188:191], v147 offset:6144
	ds_read_b128 v[192:195], v147 offset:7168
	s_add_i32 s38, 0, 0x14000
	v_add_u32_e32 v156, s38, v145
	ds_read_b128 v[196:199], v156
	ds_read_b128 v[200:203], v156 offset:1024
	ds_read_b128 v[204:207], v156 offset:2048
	ds_read_b128 v[210:213], v156 offset:3072
	s_waitcnt lgkmcnt(4)
	s_barrier
	s_waitcnt lgkmcnt(0)
	v_mfma_f32_16x16x32_bf16 v[126:129], v[140:143], v[164:167], v[126:129]
	v_mfma_f32_16x16x32_bf16 v[122:125], v[152:155], v[164:167], v[122:125]
	v_mfma_f32_16x16x32_bf16 v[118:121], v[140:143], v[172:175], v[118:121]
	v_mfma_f32_16x16x32_bf16 v[110:113], v[152:155], v[172:175], v[110:113]
	v_mfma_f32_16x16x32_bf16 v[102:105], v[140:143], v[180:183], v[102:105]
	v_mfma_f32_16x16x32_bf16 v[94:97], v[152:155], v[180:183], v[94:97]
	v_mfma_f32_16x16x32_bf16 v[86:89], v[140:143], v[188:191], v[86:89]
	v_mfma_f32_16x16x32_bf16 v[78:81], v[152:155], v[188:191], v[78:81]
	v_mfma_f32_16x16x32_bf16 v[126:129], v[148:151], v[168:171], v[126:129]
	v_mfma_f32_16x16x32_bf16 v[122:125], v[160:163], v[168:171], v[122:125]
	v_mfma_f32_16x16x32_bf16 v[118:121], v[148:151], v[176:179], v[118:121]
	v_mfma_f32_16x16x32_bf16 v[110:113], v[160:163], v[176:179], v[110:113]
	v_mfma_f32_16x16x32_bf16 v[102:105], v[148:151], v[184:187], v[102:105]
	v_mfma_f32_16x16x32_bf16 v[94:97], v[160:163], v[184:187], v[94:97]
	v_mfma_f32_16x16x32_bf16 v[86:89], v[148:151], v[192:195], v[86:89]
	v_mfma_f32_16x16x32_bf16 v[78:81], v[160:163], v[192:195], v[78:81]
	v_mfma_f32_16x16x32_bf16 v[114:117], v[196:199], v[164:167], v[114:117]
	v_mfma_f32_16x16x32_bf16 v[106:109], v[204:207], v[164:167], v[106:109]
	v_mfma_f32_16x16x32_bf16 v[98:101], v[196:199], v[172:175], v[98:101]
	v_mfma_f32_16x16x32_bf16 v[90:93], v[204:207], v[172:175], v[90:93]
	v_mfma_f32_16x16x32_bf16 v[82:85], v[196:199], v[180:183], v[82:85]
	v_mfma_f32_16x16x32_bf16 v[74:77], v[204:207], v[180:183], v[74:77]
	v_mfma_f32_16x16x32_bf16 v[70:73], v[196:199], v[188:191], v[70:73]
	v_mfma_f32_16x16x32_bf16 v[66:69], v[204:207], v[188:191], v[66:69]
	v_mfma_f32_16x16x32_bf16 v[114:117], v[200:203], v[168:171], v[114:117]
	v_mfma_f32_16x16x32_bf16 v[106:109], v[210:213], v[168:171], v[106:109]
	v_mfma_f32_16x16x32_bf16 v[98:101], v[200:203], v[176:179], v[98:101]
	v_mfma_f32_16x16x32_bf16 v[90:93], v[210:213], v[176:179], v[90:93]
	v_mfma_f32_16x16x32_bf16 v[82:85], v[200:203], v[184:187], v[82:85]
	v_mfma_f32_16x16x32_bf16 v[74:77], v[210:213], v[184:187], v[74:77]
	v_mfma_f32_16x16x32_bf16 v[70:73], v[200:203], v[192:195], v[70:73]
	v_mfma_f32_16x16x32_bf16 v[66:69], v[210:213], v[192:195], v[66:69]
	s_barrier
	s_add_i32 s39, s71, s56
	s_mov_b32 m0, s39
	s_nop 0
	global_load_lds_dwordx4 v0, s[52:53]
	s_add_i32 m0, s39, 0x2000
	s_nop 0
	global_load_lds_dwordx4 v134, s[52:53]
	s_mov_b32 m0, s29
	s_nop 0
	global_load_lds_dwordx4 v130, s[54:55]
	s_mov_b32 m0, s41
	s_nop 0
	global_load_lds_dwordx4 v132, s[54:55]
	ds_read_b128 v[164:167], v147 offset:16384
	ds_read_b128 v[168:171], v147 offset:17408
	ds_read_b128 v[172:175], v147 offset:18432
	ds_read_b128 v[176:179], v147 offset:19456
	ds_read_b128 v[180:183], v147 offset:20480
	ds_read_b128 v[184:187], v147 offset:21504
	ds_read_b128 v[188:191], v147 offset:22528
	ds_read_b128 v[192:195], v147 offset:23552
	s_cmp_lg_u32 s70, -2
	s_cbranch_scc1 .Lq2n_354
	s_cmp_eq_u32 s64, 1
	s_cbranch_scc1 .Lq2n_354
	s_waitcnt vmcnt(22)
	s_branch .Lq2d_354

; #define PG8_STAGE(bufoff, gbase, voff) do { _Pragma("unroll") for (int _i = 0; _i < 2; ++_i) \
;         __builtin_amdgcn_global_load_lds((const unsigned*)((const char*)(gbase) + (voff)[_i]), (LAS unsigned*)(lds + (bufoff) + ldsw + _i * 8192), 16, 0, 0); } while (0)
; #define PG8_LDA(dst, b, h) do { _Pragma("unroll") for (int m = 0; m < 4; ++m) _Pragma("unroll") for (int k = 0; k < 2; ++k) dst[m][k] = *(const LAS bf16x8*)(lds + PG8_SA(b, h) + aoff + m * 2048 + k * 1024); } while (0)
; #define PG8_LDB(dst, b, h) do { _Pragma("unroll") for (int n = 0; n < 2; ++n) _Pragma("unroll") for (int k = 0; k < 2; ++k) dst[n][k] = *(const LAS bf16x8*)(lds + PG8_SB(b, h) + boff + n * 2048 + k * 1024); } while (0)
; #define PG8_MMA(ai, bj, At, Bt) do { __builtin_amdgcn_s_setprio(1); _Pragma("unroll") for (int m = 0; m < 4; ++m) _Pragma("unroll") for (int n = 0; n < 2; ++n) _Pragma("unroll") for (int k = 0; k < 2; ++k) \
;         acc[ai][bj][m][n] = __builtin_amdgcn_mfma_f32_16x16x32_bf16(Bt[n][k], At[m][k], acc[ai][bj][m][n], 0, 0, 0); __builtin_amdgcn_s_setprio(0); } while (0)
; #define PG8_WAIT_V(n) asm volatile("s_waitcnt vmcnt(" #n ")" ::: "memory")
; #define PG8_WAIT_L(n) asm volatile("s_waitcnt lgkmcnt(" #n ")" ::: "memory")
; #define PG8_BAR __builtin_amdgcn_s_barrier()
; #define PG8_SCHED __builtin_amdgcn_sched_barrier(0)
; template <class Epi, class Sched>
; __device__ __forceinline__ void gemm_phase(LAS unsigned char* lds, const Gemm g, const Sched& S, const Epi& E) {
;     ...
;             PG8_BAR; PG8_WAIT_L(0); PG8_MMA(1, 0, At, B0); PG8_BAR; PG8_SCHED;
;             PG8_STAGE(PG8_SB(0, 1), b2 + hstep, voffB);
;             PG8_WAIT_V(6); PG8_BAR; PG8_MMA(1, 1, At, B1); PG8_BAR;
;             PG8_LDB(B0, 1, 0); PG8_SCHED; PG8_LDA(At, 1, 0); PG8_STAGE(PG8_SA(0, 1), a2 + hstep, voffA);
;             PG8_WAIT_L(8); PG8_BAR; PG8_WAIT_L(0); PG8_MMA(0, 0, At, B0); PG8_BAR; PG8_SCHED;
.Lq2d_354:
	s_waitcnt lgkmcnt(0)
	s_barrier
	v_mfma_f32_16x16x32_bf16 v[62:65], v[140:143], v[164:167], v[62:65]
	v_mfma_f32_16x16x32_bf16 v[58:61], v[152:155], v[164:167], v[58:61]
	v_mfma_f32_16x16x32_bf16 v[54:57], v[140:143], v[172:175], v[54:57]
	v_mfma_f32_16x16x32_bf16 v[46:49], v[152:155], v[172:175], v[46:49]
	v_mfma_f32_16x16x32_bf16 v[38:41], v[140:143], v[180:183], v[38:41]
	v_mfma_f32_16x16x32_bf16 v[30:33], v[152:155], v[180:183], v[30:33]
	v_mfma_f32_16x16x32_bf16 v[22:25], v[140:143], v[188:191], v[22:25]
	v_mfma_f32_16x16x32_bf16 v[14:17], v[152:155], v[188:191], v[14:17]
	v_mfma_f32_16x16x32_bf16 v[62:65], v[148:151], v[168:171], v[62:65]
	v_mfma_f32_16x16x32_bf16 v[58:61], v[160:163], v[168:171], v[58:61]
	v_mfma_f32_16x16x32_bf16 v[54:57], v[148:151], v[176:179], v[54:57]
	v_mfma_f32_16x16x32_bf16 v[46:49], v[160:163], v[176:179], v[46:49]
	v_mfma_f32_16x16x32_bf16 v[38:41], v[148:151], v[184:187], v[38:41]
	v_mfma_f32_16x16x32_bf16 v[30:33], v[160:163], v[184:187], v[30:33]
	v_mfma_f32_16x16x32_bf16 v[22:25], v[148:151], v[192:195], v[22:25]
	v_mfma_f32_16x16x32_bf16 v[14:17], v[160:163], v[192:195], v[14:17]
	v_mfma_f32_16x16x32_bf16 v[50:53], v[196:199], v[164:167], v[50:53]
	v_mfma_f32_16x16x32_bf16 v[42:45], v[204:207], v[164:167], v[42:45]
	v_mfma_f32_16x16x32_bf16 v[34:37], v[196:199], v[172:175], v[34:37]
	v_mfma_f32_16x16x32_bf16 v[26:29], v[204:207], v[172:175], v[26:29]
	v_mfma_f32_16x16x32_bf16 v[18:21], v[196:199], v[180:183], v[18:21]
	v_mfma_f32_16x16x32_bf16 v[10:13], v[204:207], v[180:183], v[10:13]
	v_mfma_f32_16x16x32_bf16 v[6:9], v[196:199], v[188:191], v[6:9]
	v_mfma_f32_16x16x32_bf16 v[2:5], v[204:207], v[188:191], v[2:5]
	v_mfma_f32_16x16x32_bf16 v[50:53], v[200:203], v[168:171], v[50:53]
	v_mfma_f32_16x16x32_bf16 v[42:45], v[210:213], v[168:171], v[42:45]
	v_mfma_f32_16x16x32_bf16 v[34:37], v[200:203], v[176:179], v[34:37]
	v_mfma_f32_16x16x32_bf16 v[26:29], v[210:213], v[176:179], v[26:29]
	v_mfma_f32_16x16x32_bf16 v[18:21], v[200:203], v[184:187], v[18:21]
	v_mfma_f32_16x16x32_bf16 v[10:13], v[210:213], v[184:187], v[10:13]
	v_mfma_f32_16x16x32_bf16 v[6:9], v[200:203], v[192:195], v[6:9]
	v_mfma_f32_16x16x32_bf16 v[2:5], v[210:213], v[192:195], v[2:5]
	s_barrier
	s_add_u32 s72, s52, 0x80000
	s_addc_u32 s73, s53, 0
	s_add_i32 s38, s38, s56
	s_mov_b32 m0, s38
	s_nop 0
	global_load_lds_dwordx4 v0, s[72:73]
	s_add_i32 m0, s38, 0x2000
	s_nop 0
	global_load_lds_dwordx4 v134, s[72:73]
	s_add_u32 s54, s54, 0x80000
	s_addc_u32 s55, s55, 0
	s_mov_b32 m0, s57
	s_nop 0
	global_load_lds_dwordx4 v130, s[54:55]
	s_mov_b32 m0, s58
	s_nop 0
	global_load_lds_dwordx4 v132, s[54:55]
	s_add_i32 s38, 0, 0x18000
	v_add_u32_e32 v160, s38, v145
	ds_read_b128 v[140:143], v160
	ds_read_b128 v[148:151], v160 offset:1024
	ds_read_b128 v[152:155], v160 offset:2048
	ds_read_b128 v[160:163], v160 offset:3072
	ds_read_b128 v[164:167], v147 offset:32768
	ds_read_b128 v[168:171], v147 offset:33792
	ds_read_b128 v[172:175], v147 offset:34816
	ds_read_b128 v[176:179], v147 offset:35840
	ds_read_b128 v[180:183], v147 offset:36864
	ds_read_b128 v[184:187], v147 offset:37888
	ds_read_b128 v[188:191], v147 offset:38912
	ds_read_b128 v[192:195], v147 offset:39936
	s_add_i32 s39, 0, 0x1c000
	v_add_u32_e32 v210, s39, v145
	ds_read_b128 v[196:199], v210
	ds_read_b128 v[200:203], v210 offset:1024
	ds_read_b128 v[204:207], v210 offset:2048
	ds_read_b128 v[210:213], v210 offset:3072
	s_waitcnt lgkmcnt(4)
	s_barrier
	s_waitcnt lgkmcnt(0)
	v_mfma_f32_16x16x32_bf16 v[126:129], v[140:143], v[164:167], v[126:129]
	v_mfma_f32_16x16x32_bf16 v[122:125], v[152:155], v[164:167], v[122:125]
	v_mfma_f32_16x16x32_bf16 v[118:121], v[140:143], v[172:175], v[118:121]
	v_mfma_f32_16x16x32_bf16 v[110:113], v[152:155], v[172:175], v[110:113]
	v_mfma_f32_16x16x32_bf16 v[102:105], v[140:143], v[180:183], v[102:105]
	v_mfma_f32_16x16x32_bf16 v[94:97], v[152:155], v[180:183], v[94:97]
	v_mfma_f32_16x16x32_bf16 v[86:89], v[140:143], v[188:191], v[86:89]
	v_mfma_f32_16x16x32_bf16 v[78:81], v[152:155], v[188:191], v[78:81]
	v_mfma_f32_16x16x32_bf16 v[126:129], v[148:151], v[168:171], v[126:129]
	v_mfma_f32_16x16x32_bf16 v[122:125], v[160:163], v[168:171], v[122:125]
	v_mfma_f32_16x16x32_bf16 v[118:121], v[148:151], v[176:179], v[118:121]
	v_mfma_f32_16x16x32_bf16 v[110:113], v[160:163], v[176:179], v[110:113]
	v_mfma_f32_16x16x32_bf16 v[102:105], v[148:151], v[184:187], v[102:105]
	v_mfma_f32_16x16x32_bf16 v[94:97], v[160:163], v[184:187], v[94:97]
	v_mfma_f32_16x16x32_bf16 v[86:89], v[148:151], v[192:195], v[86:89]
	v_mfma_f32_16x16x32_bf16 v[78:81], v[160:163], v[192:195], v[78:81]
	v_mfma_f32_16x16x32_bf16 v[114:117], v[196:199], v[164:167], v[114:117]
	v_mfma_f32_16x16x32_bf16 v[106:109], v[204:207], v[164:167], v[106:109]
	v_mfma_f32_16x16x32_bf16 v[98:101], v[196:199], v[172:175], v[98:101]
	v_mfma_f32_16x16x32_bf16 v[90:93], v[204:207], v[172:175], v[90:93]
	v_mfma_f32_16x16x32_bf16 v[82:85], v[196:199], v[180:183], v[82:85]
	v_mfma_f32_16x16x32_bf16 v[74:77], v[204:207], v[180:183], v[74:77]
	v_mfma_f32_16x16x32_bf16 v[70:73], v[196:199], v[188:191], v[70:73]
	v_mfma_f32_16x16x32_bf16 v[66:69], v[204:207], v[188:191], v[66:69]
	v_mfma_f32_16x16x32_bf16 v[114:117], v[200:203], v[168:171], v[114:117]
	v_mfma_f32_16x16x32_bf16 v[106:109], v[210:213], v[168:171], v[106:109]
	v_mfma_f32_16x16x32_bf16 v[98:101], v[200:203], v[176:179], v[98:101]
	v_mfma_f32_16x16x32_bf16 v[90:93], v[210:213], v[176:179], v[90:93]
	v_mfma_f32_16x16x32_bf16 v[82:85], v[200:203], v[184:187], v[82:85]
	v_mfma_f32_16x16x32_bf16 v[74:77], v[210:213], v[184:187], v[74:77]
	v_mfma_f32_16x16x32_bf16 v[70:73], v[200:203], v[192:195], v[70:73]
	v_mfma_f32_16x16x32_bf16 v[66:69], v[210:213], v[192:195], v[66:69]
	s_barrier
; #define PG8_STAGE(bufoff, gbase, voff) do { _Pragma("unroll") for (int _i = 0; _i < 2; ++_i) \
;         __builtin_amdgcn_global_load_lds((const unsigned*)((const char*)(gbase) + (voff)[_i]), (LAS unsigned*)(lds + (bufoff) + ldsw + _i * 8192), 16, 0, 0); } while (0)
; #define PG8_LDA(dst, b, h) do { _Pragma("unroll") for (int m = 0; m < 4; ++m) _Pragma("unroll") for (int k = 0; k < 2; ++k) dst[m][k] = *(const LAS bf16x8*)(lds + PG8_SA(b, h) + aoff + m * 2048 + k * 1024); } while (0)
; #define PG8_WAIT_V(n) asm volatile("s_waitcnt vmcnt(" #n ")" ::: "memory")
; #define PG8_WAIT_L(n) asm volatile("s_waitcnt lgkmcnt(" #n ")" ::: "memory")
; template <class Epi, class Sched>
; __device__ __forceinline__ void gemm_phase(LAS unsigned char* lds, const Gemm g, const Sched& S, const Epi& E) {
;     ...
;         for (int t = 0; t < nt; t += 2) {
;             const bool last = (t == nt - 2);
;             const char* a1 = cA + (size_t)(t + 1) * kstep;
;             const char* a2 = last ? nA : cA + (size_t)(t + 2) * kstep; const char* b2 = last ? nB : cB + (size_t)(t + 2) * kstep;
;             const char* a3 = a2 + kstep; const char* b3 = b2 + kstep;
;             PG8_LDB(B0, 0, 0); PG8_SCHED; PG8_LDA(At, 0, 0); PG8_STAGE(PG8_SA(1, 1), a1 + hstep, voffA);
;             PG8_WAIT_L(8); PG8_BAR; PG8_WAIT_L(0); PG8_MMA(0, 0, At, B0); PG8_BAR; PG8_SCHED;
;             PG8_LDB(B1, 0, 1); PG8_STAGE(PG8_SB(0, 0), b2, voffB);
;             PG8_BAR; PG8_WAIT_L(0); PG8_MMA(0, 1, At, B1); PG8_BAR;
;             PG8_LDA(At, 0, 1); PG8_STAGE(PG8_SA(0, 0), a2, voffA);
;             PG8_BAR; PG8_WAIT_L(0); PG8_MMA(1, 0, At, B0); PG8_BAR; PG8_SCHED;
;             PG8_STAGE(PG8_SB(0, 1), b2 + hstep, voffB);
;             PG8_WAIT_V(6); PG8_BAR; PG8_MMA(1, 1, At, B1); PG8_BAR;
;             PG8_LDB(B0, 1, 0); PG8_SCHED; PG8_LDA(At, 1, 0); PG8_STAGE(PG8_SA(0, 1), a2 + hstep, voffA);
;             PG8_WAIT_L(8); PG8_BAR; PG8_WAIT_L(0); PG8_MMA(0, 0, At, B0); PG8_BAR; PG8_SCHED;
;             PG8_LDB(B1, 1, 1); PG8_STAGE(PG8_SB(1, 0), b3, voffB);
;             PG8_BAR; PG8_WAIT_L(0); PG8_MMA(0, 1, At, B1); PG8_BAR;
;             PG8_LDA(At, 1, 1); PG8_STAGE(PG8_SA(1, 0), a3, voffA);
;             PG8_BAR; PG8_WAIT_L(0); PG8_MMA(1, 0, At, B0); PG8_BAR; PG8_SCHED;
;             PG8_STAGE(PG8_SB(1, 1), b3 + hstep, voffB);
;             PG8_WAIT_V(6); PG8_BAR; PG8_MMA(1, 1, At, B1); PG8_BAR;
	s_add_i32 s38, s38, s56
	s_add_u32 s100, s52, s36
	s_addc_u32 s101, s53, s37
	s_mov_b32 m0, s38
	s_nop 0
	global_load_lds_dwordx4 v0, s[100:101]
	s_add_i32 m0, s38, 0x2000
	s_nop 0
	global_load_lds_dwordx4 v134, s[100:101]
	s_mov_b32 m0, s59
	s_add_u32 s100, s54, s36
	s_addc_u32 s101, s55, s37
	s_sub_u32 s100, s100, 0x80000
	s_subb_u32 s101, s101, 0
	global_load_lds_dwordx4 v130, s[100:101]
	s_mov_b32 m0, s60
	s_nop 0
	global_load_lds_dwordx4 v132, s[100:101]
	ds_read_b128 v[164:167], v147 offset:49152
	ds_read_b128 v[168:171], v147 offset:50176
	ds_read_b128 v[172:175], v147 offset:51200
	ds_read_b128 v[176:179], v147 offset:52224
	ds_read_b128 v[180:183], v147 offset:53248
	ds_read_b128 v[184:187], v147 offset:54272
	ds_read_b128 v[188:191], v147 offset:55296
	ds_read_b128 v[192:195], v147 offset:56320
	s_waitcnt vmcnt(4)
	s_waitcnt lgkmcnt(0)
	s_barrier
	v_mfma_f32_16x16x32_bf16 v[62:65], v[140:143], v[164:167], v[62:65]
	v_mfma_f32_16x16x32_bf16 v[58:61], v[152:155], v[164:167], v[58:61]
	v_mfma_f32_16x16x32_bf16 v[54:57], v[140:143], v[172:175], v[54:57]
	v_mfma_f32_16x16x32_bf16 v[46:49], v[152:155], v[172:175], v[46:49]
	v_mfma_f32_16x16x32_bf16 v[38:41], v[140:143], v[180:183], v[38:41]
	v_mfma_f32_16x16x32_bf16 v[30:33], v[152:155], v[180:183], v[30:33]
	v_mfma_f32_16x16x32_bf16 v[22:25], v[140:143], v[188:191], v[22:25]
	v_mfma_f32_16x16x32_bf16 v[14:17], v[152:155], v[188:191], v[14:17]
	v_mfma_f32_16x16x32_bf16 v[62:65], v[148:151], v[168:171], v[62:65]
	v_mfma_f32_16x16x32_bf16 v[58:61], v[160:163], v[168:171], v[58:61]
	v_mfma_f32_16x16x32_bf16 v[54:57], v[148:151], v[176:179], v[54:57]
	v_mfma_f32_16x16x32_bf16 v[46:49], v[160:163], v[176:179], v[46:49]
	v_mfma_f32_16x16x32_bf16 v[38:41], v[148:151], v[184:187], v[38:41]
	v_mfma_f32_16x16x32_bf16 v[30:33], v[160:163], v[184:187], v[30:33]
	v_mfma_f32_16x16x32_bf16 v[22:25], v[148:151], v[192:195], v[22:25]
	v_mfma_f32_16x16x32_bf16 v[14:17], v[160:163], v[192:195], v[14:17]
	s_add_u32 s52, s52, 0x80080
	s_addc_u32 s53, s53, 0
	s_add_i32 s38, s39, s56
	s_mov_b32 m0, s38
	s_nop 0
	global_load_lds_dwordx4 v0, s[52:53]
	s_add_i32 m0, s38, 0x2000
	s_nop 0
	global_load_lds_dwordx4 v134, s[52:53]
	v_mfma_f32_16x16x32_bf16 v[50:53], v[196:199], v[164:167], v[50:53]
	v_mfma_f32_16x16x32_bf16 v[42:45], v[204:207], v[164:167], v[42:45]
	v_mfma_f32_16x16x32_bf16 v[34:37], v[196:199], v[172:175], v[34:37]
	v_mfma_f32_16x16x32_bf16 v[26:29], v[204:207], v[172:175], v[26:29]
	v_mfma_f32_16x16x32_bf16 v[18:21], v[196:199], v[180:183], v[18:21]
	v_mfma_f32_16x16x32_bf16 v[10:13], v[204:207], v[180:183], v[10:13]
	v_mfma_f32_16x16x32_bf16 v[6:9], v[196:199], v[188:191], v[6:9]
	v_mfma_f32_16x16x32_bf16 v[2:5], v[204:207], v[188:191], v[2:5]
	v_mfma_f32_16x16x32_bf16 v[50:53], v[200:203], v[168:171], v[50:53]
	v_mfma_f32_16x16x32_bf16 v[42:45], v[210:213], v[168:171], v[42:45]
	v_mfma_f32_16x16x32_bf16 v[34:37], v[200:203], v[176:179], v[34:37]
	v_mfma_f32_16x16x32_bf16 v[26:29], v[210:213], v[176:179], v[26:29]
	v_mfma_f32_16x16x32_bf16 v[18:21], v[200:203], v[184:187], v[18:21]
	v_mfma_f32_16x16x32_bf16 v[10:13], v[210:213], v[184:187], v[10:13]
	v_mfma_f32_16x16x32_bf16 v[6:9], v[200:203], v[192:195], v[6:9]
	v_mfma_f32_16x16x32_bf16 v[2:5], v[210:213], v[192:195], v[2:5]
	s_add_i32 s70, s70, 2
	s_add_u32 s68, s68, 0x100
	s_addc_u32 s69, s69, 0
	s_add_u32 s50, s50, 0x100
	s_addc_u32 s51, s51, 0
	s_cmp_gt_u32 s70, 29
	s_barrier
	s_cbranch_scc0 .LBB0_354
	s_cmp_lg_u64 s[46:47], 0
	s_cbranch_scc1 .Lnoh_354
	s_add_u32 s100, s44, 0x80080
	s_addc_u32 s101, s45, 0
	s_add_i32 m0, s29, 0xc000
	s_nop 0
	global_load_lds_dwordx4 v138, s[100:101]
	s_add_i32 m0, s29, 0xe000
	s_nop 0
	global_load_lds_dwordx4 v136, s[100:101]
